# baseline (speedup 1.0000x reference)
; __device__ __forceinline__ int ltid() { int t = threadIdx.x; asm volatile("" : "+v"(t)); return t; }
; __device__ __forceinline__ void emit_p(const float* stage, u16* dst, const float* aj, const float* Ai, int doff) {
;   const int tid = ltid(), c4 = (tid & 31) * 4, rr = tid >> 5;
;   const float4 a0 = *(const float4*)(aj + c4), a1 = *(const float4*)(aj + 128 + c4);
;   const float av[8] = {a0.x, a0.y, a0.z, a0.w, a1.x, a1.y, a1.z, a1.w};
; #pragma unroll 1
;   for (int ps = 0; ps < 8; ++ps) {
;     const int r = ps * 16 + rr;
;     const float* s = stage + r * SP + c4;
;     const float4 a = *(const float4*)s, b = *(const float4*)(s + 128);
;     float v[8] = {a.x, a.y, a.z, a.w, b.x, b.y, b.z, b.w};
;     const float A = Ai[r];
; #pragma unroll
;     for (int e = 0; e < 8; ++e) {
;       const int c = (e < 4) ? (c4 + e) : (128 + c4 + e - 4);
;       v[e] = (c <= r + doff) ? v[e] * __expf(av[e] - A) : 0.f;
;     }
;     uint2 o0, o1;
;     o0.x = pack2(v[0], v[1]); o0.y = pack2(v[2], v[3]); o1.x = pack2(v[4], v[5]); o1.y = pack2(v[6], v[7]);
;     *(uint2*)(dst + (long)r * 2048 + c4) = o0;
;     *(uint2*)(dst + (long)r * 2048 + 128 + c4) = o1;
;   }
; }
; __device__ __forceinline__ void s_decode(int t, int& tb, int& tc, int& ti, int& tj) {
;   tb = t / 144; int rem = t % 144; tc = rem / 36; int tri = rem % 36;
;   ti = 0; while ((ti + 1) * (ti + 2) / 2 <= tri) ++ti;
;   tj = tri - ti * (ti + 1) / 2;
; }
.LBB0_529:
	s_mov_b32 s8, s6
	s_mov_b32 s52, s7
	s_add_i32 s6, s5, 2
	s_add_i32 s7, s5, 3
	s_mul_i32 s6, s6, s7
	s_mov_b32 s9, s10
	s_lshr_b32 s11, s6, 1
	s_add_i32 s5, s5, 1
	s_add_i32 s6, s8, 1
	s_add_i32 s24, s1, 2
	s_add_i32 s10, s10, s1
	s_add_i32 s7, s52, 0x100
	s_cmp_le_i32 s11, s22
	s_mov_b32 s1, s24
	s_cbranch_scc1 .LBB0_529
	s_add_i32 s1, s5, 1
	s_mul_i32 s1, s1, s5
	s_lshr_b32 s1, s1, 1
	s_sext_i32_i16 s6, s4
	s_sub_i32 s4, s22, s1
	s_lshl_b32 s27, s0, 15
	s_lshl_b32 s30, s4, 8
	s_add_i32 s4, s27, s20
	s_ashr_i32 s1, s0, 31
	s_ashr_i32 s7, s6, 31
	s_ashr_i32 s5, s4, 31
	s_lshl_b64 s[10:11], s[0:1], 13
	s_lshl_b64 s[28:29], s[6:7], 11
	s_ashr_i32 s31, s30, 31
	s_lshl_b64 s[4:5], s[4:5], 2
	s_add_u32 s24, s14, s4
	s_addc_u32 s26, s15, s5
	s_lshl_b32 s4, s6, 11
	s_ashr_i32 s5, s4, 31
	s_lshl_b64 s[4:5], s[4:5], 2
	s_add_u32 s25, s24, s4
	v_mov_b32_e32 v84, v139
	s_addc_u32 s26, s26, s5
	s_lshl_b64 s[30:31], s[30:31], 2
	s_add_u32 s30, s25, s30
	v_lshlrev_b32_e32 v0, 2, v84
	v_and_b32_e32 v82, 0x7c, v0
	s_addc_u32 s31, s26, s31
	v_lshlrev_b32_e32 v0, 2, v82
	v_lshl_add_u64 v[2:3], s[30:31], 0, v[0:1]
	global_load_dwordx4 v[68:71], v[2:3], off
	global_load_dwordx4 v[72:75], v[2:3], off offset:512
	s_lshr_b32 s30, s9, 1
	v_ashrrev_i32_e32 v76, 5, v84
	s_add_i32 s8, s8, s30
	v_lshl_add_u32 v90, s8, 8, v76
	s_add_u32 s8, s10, s28
	s_addc_u32 s9, s11, s29
	s_add_u32 s8, s8, s52
	s_addc_u32 s9, s9, 0
	s_lshl_b32 s24, s22, 8
	s_lshl_b32 s10, s30, 8
	s_sub_i32 s10, s24, s10
	s_ashr_i32 s11, s10, 31
	v_ashrrev_i32_e32 v77, 31, v76
	s_lshl_b64 s[8:9], s[8:9], 12
	s_lshl_b64 s[10:11], s[10:11], 1
	v_lshlrev_b64 v[78:79], 12, v[76:77]
	v_and_b32_e32 v86, 31, v84
	s_add_u32 s8, s10, s8
	v_lshl_or_b32 v78, v86, 3, v78
	s_addc_u32 s9, s11, s9
	v_lshl_add_u64 v[84:85], s[8:9], 0, v[78:79]
	s_add_i32 s8, s17, s27
	s_ashr_i32 s9, s8, 31
	s_lshl_b64 s[8:9], s[8:9], 2
	s_lshl_b64 s[10:11], s[52:53], 2
	s_add_u32 s10, s10, s8
	s_addc_u32 s11, s11, s9
	s_add_u32 s10, s10, s4
	s_addc_u32 s11, s11, s5
	v_mul_lo_u32 v78, v76, s81
	v_lshlrev_b32_e32 v79, 4, v86
	v_lshl_add_u64 v[76:77], v[76:77], 2, s[10:11]
	s_mov_b64 s[10:11], 0x436c0000
	v_or_b32_e32 v3, 3, v82
	v_or_b32_e32 v0, 2, v82
	v_or_b32_e32 v81, 0x81, v82
	v_or_b32_e32 v2, 0x80, v82
	v_or_b32_e32 v83, 0x83, v82
	v_or_b32_e32 v80, 0x82, v82
	v_add3_u32 v91, v78, v79, 16
	v_lshl_add_u64 v[86:87], v[76:77], 0, s[10:11]
	s_mov_b32 s27, 0
	s_mov_b32 s30, 0xc400000
	v_lshl_add_u64 v[174:175], s[66:67], 0, v[86:87]
	global_load_dword v172, v[174:175], off
	s_waitcnt vmcnt(0)
	s_branch .LBB0_532
.LBB0_531:
	s_or_b64 exec, exec, s[10:11]
	s_waitcnt lgkmcnt(0)
	v_sub_f32_e32 v95, v69, v93
	v_mul_f32_e32 v95, 0x3fb8aa3b, v95
	v_exp_f32_e32 v95, v95
	v_cmp_lt_i32_e32 vcc, v82, v90
	s_addk_i32 s27, 0x4100
	s_mov_b64 s[10:11], 0x10000
	v_mul_f32_e32 v94, v94, v95
	v_cndmask_b32_e32 v96, 0, v94, vcc
	v_sub_f32_e32 v94, v70, v93
	v_sub_f32_e32 v95, v71, v93
	v_mul_f32_e32 v94, 0x3fb8aa3b, v94
	v_mul_f32_e32 v95, 0x3fb8aa3b, v95
	v_exp_f32_e32 v94, v94
	v_exp_f32_e32 v95, v95
	v_cmp_le_i32_e32 vcc, v0, v90
	v_cvt_pk_bf16_f32 v92, v92, v96
	v_lshl_add_u64 v[86:87], v[86:87], 0, 64
	v_pk_mul_f32 v[88:89], v[88:89], v[94:95]
	v_sub_f32_e32 v94, v72, v93
	v_sub_f32_e32 v95, v73, v93
	v_mul_f32_e32 v94, 0x3fb8aa3b, v94
	v_mul_f32_e32 v95, 0x3fb8aa3b, v95
	v_exp_f32_e32 v94, v94
	v_exp_f32_e32 v95, v95
	v_cvt_pk_bf16_f32 v88, v88, v89
	v_cndmask_b32_e32 v89, 0, v88, vcc
	v_lshrrev_b32_e32 v88, 16, v88
	v_pk_mul_f32 v[76:77], v[76:77], v[94:95]
	v_sub_f32_e32 v94, v74, v93
	v_sub_f32_e32 v93, v75, v93
	v_mul_f32_e32 v94, 0x3fb8aa3b, v94
	v_mul_f32_e32 v93, 0x3fb8aa3b, v93
	v_exp_f32_e32 v94, v94
	v_exp_f32_e32 v95, v93
	v_cmp_le_i32_e32 vcc, v3, v90
	v_cvt_pk_bf16_f32 v76, v76, v77
	s_cmp_lg_u32 s27, 0x20800
	v_cndmask_b32_e32 v88, 0, v88, vcc
	v_cmp_le_i32_e32 vcc, v2, v90
	v_pk_mul_f32 v[78:79], v[78:79], v[94:95]
	v_perm_b32 v93, v88, v89, s59
	v_cndmask_b32_e32 v88, 0, v76, vcc
	v_lshrrev_b32_e32 v76, 16, v76
	v_cmp_le_i32_e32 vcc, v81, v90
	s_nop 1
	v_cndmask_b32_e32 v89, 0, v76, vcc
	v_cvt_pk_bf16_f32 v76, v78, v79
	v_cmp_le_i32_e32 vcc, v80, v90
	s_nop 1
	v_cndmask_b32_e32 v78, 0, v76, vcc
	v_lshrrev_b32_e32 v76, 16, v76
	v_cmp_le_i32_e32 vcc, v83, v90
	v_add_u32_e32 v90, 16, v90
	s_nop 0
	v_cndmask_b32_e32 v79, 0, v76, vcc
	v_lshl_add_u64 v[76:77], s[66:67], 0, v[84:85]
	v_add_co_u32_e32 v76, vcc, s30, v76
	v_perm_b32 v79, v79, v78, s59
	s_nop 0
	v_addc_co_u32_e32 v77, vcc, 0, v77, vcc
	v_perm_b32 v78, v89, v88, s59
	v_lshl_add_u64 v[84:85], v[84:85], 0, s[10:11]
	v_lshl_add_u64 v[174:175], s[66:67], 0, v[86:87]
	global_load_dword v172, v[174:175], off
	global_store_dwordx2 v[76:77], v[92:93], off
	global_store_dwordx2 v[76:77], v[78:79], off offset:256
	s_cbranch_scc0 .LBB0_534
.LBB0_532:
	s_waitcnt vmcnt(2)
	v_mov_b32_e32 v93, v172
	v_add_u32_e32 v95, s27, v91
	ds_read_b32 v94, v95 offset:4
	ds_read_b64 v[88:89], v95 offset:8
	ds_read_b128 v[76:79], v95 offset:512
	v_cmp_le_i32_e32 vcc, v82, v90
	v_mov_b32_e32 v92, 0
	s_and_saveexec_b64 s[10:11], vcc
	s_cbranch_execz .LBB0_531
	s_waitcnt lgkmcnt(0)
	v_sub_f32_e32 v92, v68, v93
	v_mul_f32_e32 v92, 0x3fb8aa3b, v92
	ds_read_b32 v95, v95
	v_exp_f32_e32 v92, v92
	s_waitcnt lgkmcnt(0)
	v_mul_f32_e32 v92, v92, v95
	s_branch .LBB0_531

; __device__ __forceinline__ int ltid() { int t = threadIdx.x; asm volatile("" : "+v"(t)); return t; }
; __device__ __forceinline__ void emit_p(const float* stage, u16* dst, const float* aj, const float* Ai, int doff) {
;   const int tid = ltid(), c4 = (tid & 31) * 4, rr = tid >> 5;
;   const float4 a0 = *(const float4*)(aj + c4), a1 = *(const float4*)(aj + 128 + c4);
;   const float av[8] = {a0.x, a0.y, a0.z, a0.w, a1.x, a1.y, a1.z, a1.w};
; #pragma unroll 1
;   for (int ps = 0; ps < 8; ++ps) {
;     const int r = ps * 16 + rr;
;     const float* s = stage + r * SP + c4;
;     const float4 a = *(const float4*)s, b = *(const float4*)(s + 128);
;     float v[8] = {a.x, a.y, a.z, a.w, b.x, b.y, b.z, b.w};
;     const float A = Ai[r];
; #pragma unroll
;     for (int e = 0; e < 8; ++e) {
;       const int c = (e < 4) ? (c4 + e) : (128 + c4 + e - 4);
;       v[e] = (c <= r + doff) ? v[e] * __expf(av[e] - A) : 0.f;
;     }
;     uint2 o0, o1;
;     o0.x = pack2(v[0], v[1]); o0.y = pack2(v[2], v[3]); o1.x = pack2(v[4], v[5]); o1.y = pack2(v[6], v[7]);
;     *(uint2*)(dst + (long)r * 2048 + c4) = o0;
;     *(uint2*)(dst + (long)r * 2048 + 128 + c4) = o1;
;   }
; }
; template <int KIND>
; __device__ __forceinline__ void tile_emit(const Ctx& p, int t, int hd, int s, int half, const float* stage) {
;     ...
;   } else if (KIND == G_S) {
;     int tb, tc, ti, tj; s_decode(t, tb, tc, ti, tj);
;     const int bh = tb * 4 + hd;
;     const float* ga = (const float*)(ws + OFF_GA);
;     const float* gA = (const float*)(ws + OFF_GAA);
;     emit_p(stage, (u16*)(ws + OFF_PH) + (((long)tb * 4 + tc) * 2048 + ti * 256 + hr) * 2048 + tj * 256,
;            ga + bh * SEQ + tc * 2048 + tj * 256, gA + bh * SEQ + tc * 2048 + ti * 256 + hr, (ti - tj) * 256 + hr);
.LBB0_535:
	s_mov_b32 s11, s23
	s_mov_b32 s52, s29
	s_add_i32 s23, s28, 2
	s_add_i32 s29, s28, 3
	s_mul_i32 s23, s23, s29
	s_mov_b32 s27, s30
	s_lshr_b32 s31, s23, 1
	s_add_i32 s28, s28, 1
	s_add_i32 s23, s11, 1
	s_add_i32 s34, s10, 2
	s_add_i32 s30, s30, s10
	s_add_i32 s29, s52, 0x100
	s_cmp_le_i32 s31, s22
	s_mov_b32 s10, s34
	s_cbranch_scc1 .LBB0_535
	s_add_i32 s10, s28, 1
	s_mul_i32 s10, s10, s28
	s_lshr_b32 s10, s10, 1
	s_sub_i32 s10, s22, s10
	s_lshl_b32 s22, s10, 8
	s_ashr_i32 s23, s22, 31
	v_mov_b32_e32 v20, v139
	s_lshl_b64 s[22:23], s[22:23], 2
	s_add_u32 s22, s25, s22
	v_lshlrev_b32_e32 v0, 2, v20
	v_and_b32_e32 v18, 0x7c, v0
	s_addc_u32 s23, s26, s23
	v_lshlrev_b32_e32 v0, 2, v18
	v_lshl_add_u64 v[6:7], s[22:23], 0, v[0:1]
	global_load_dwordx4 v[2:5], v[6:7], off
	s_nop 0
	global_load_dwordx4 v[6:9], v[6:7], off offset:512
	s_lshr_b32 s10, s27, 1
	s_add_i32 s11, s11, s10
	s_lshl_b64 s[0:1], s[0:1], 25
	s_lshl_b64 s[6:7], s[6:7], 23
	v_ashrrev_i32_e32 v10, 5, v20
	s_add_u32 s0, s0, s6
	v_lshl_add_u32 v11, s11, 8, v10
	s_addc_u32 s1, s1, s7
	s_lshl_b32 s6, s10, 8
	v_add_u32_e32 v26, 0x80, v11
	v_ashrrev_i32_e32 v11, 31, v10
	s_sub_i32 s6, s24, s6
	v_lshlrev_b64 v[12:13], 12, v[10:11]
	s_ashr_i32 s7, s6, 31
	v_lshl_add_u64 v[12:13], s[0:1], 0, v[12:13]
	s_lshl_b64 s[0:1], s[52:53], 12
	s_lshl_b64 s[6:7], s[6:7], 1
	v_and_b32_e32 v22, 31, v20
	s_add_u32 s0, s6, s0
	v_lshl_or_b32 v12, v22, 3, v12
	s_addc_u32 s1, s7, s1
	v_lshl_add_u64 v[20:21], s[0:1], 0, v[12:13]
	s_lshl_b64 s[0:1], s[52:53], 2
	s_add_u32 s0, s0, s8
	s_addc_u32 s1, s1, s9
	s_add_u32 s0, s0, s4
	s_addc_u32 s1, s1, s5
	v_mul_lo_u32 v12, v10, s81
	v_lshlrev_b32_e32 v13, 4, v22
	v_lshl_add_u64 v[10:11], v[10:11], 2, s[0:1]
	s_mov_b64 s[0:1], 0x436c0200
	v_or_b32_e32 v15, 3, v18
	v_or_b32_e32 v0, 2, v18
	v_or_b32_e32 v17, 0x81, v18
	v_or_b32_e32 v14, 0x80, v18
	v_or_b32_e32 v19, 0x83, v18
	v_or_b32_e32 v16, 0x82, v18
	v_add3_u32 v27, v12, v13, 16
	v_lshl_add_u64 v[22:23], v[10:11], 0, s[0:1]
	s_mov_b32 s4, 0
	s_movk_i32 s52, 0x840
	v_lshl_add_u64 v[174:175], s[66:67], 0, v[22:23]
	global_load_dword v172, v[174:175], off
	s_waitcnt vmcnt(0)
	s_branch .LBB0_538
.LBB0_537:
	s_or_b64 exec, exec, s[0:1]
	s_waitcnt lgkmcnt(0)
	v_sub_f32_e32 v31, v3, v29
	v_mul_f32_e32 v31, 0x3fb8aa3b, v31
	v_exp_f32_e32 v31, v31
	v_cmp_lt_i32_e32 vcc, v18, v26
	s_mov_b32 s0, 0xc480000
	s_addk_i32 s4, 0x4100
	v_mul_f32_e32 v30, v30, v31
	v_cndmask_b32_e32 v32, 0, v30, vcc
	v_sub_f32_e32 v30, v4, v29
	v_sub_f32_e32 v31, v5, v29
	v_mul_f32_e32 v30, 0x3fb8aa3b, v30
	v_mul_f32_e32 v31, 0x3fb8aa3b, v31
	v_exp_f32_e32 v30, v30
	v_exp_f32_e32 v31, v31
	v_cmp_le_i32_e32 vcc, v0, v26
	v_cvt_pk_bf16_f32 v28, v28, v32
	v_lshl_add_u64 v[22:23], v[22:23], 0, 64
	v_pk_mul_f32 v[24:25], v[24:25], v[30:31]
	v_sub_f32_e32 v30, v6, v29
	v_sub_f32_e32 v31, v7, v29
	v_mul_f32_e32 v30, 0x3fb8aa3b, v30
	v_mul_f32_e32 v31, 0x3fb8aa3b, v31
	v_exp_f32_e32 v30, v30
	v_exp_f32_e32 v31, v31
	v_cvt_pk_bf16_f32 v24, v24, v25
	v_cndmask_b32_e32 v25, 0, v24, vcc
	v_lshrrev_b32_e32 v24, 16, v24
	v_pk_mul_f32 v[10:11], v[10:11], v[30:31]
	v_sub_f32_e32 v30, v8, v29
	v_sub_f32_e32 v29, v9, v29
	v_mul_f32_e32 v30, 0x3fb8aa3b, v30
	v_mul_f32_e32 v29, 0x3fb8aa3b, v29
	v_exp_f32_e32 v30, v30
	v_exp_f32_e32 v31, v29
	v_cmp_le_i32_e32 vcc, v15, v26
	v_cvt_pk_bf16_f32 v10, v10, v11
	s_cmp_lg_u32 s4, 0x20800
	v_cndmask_b32_e32 v24, 0, v24, vcc
	v_cmp_le_i32_e32 vcc, v14, v26
	v_pk_mul_f32 v[12:13], v[12:13], v[30:31]
	v_perm_b32 v29, v24, v25, s59
	v_cndmask_b32_e32 v24, 0, v10, vcc
	v_lshrrev_b32_e32 v10, 16, v10
	v_cmp_le_i32_e32 vcc, v17, v26
	s_nop 1
	v_cndmask_b32_e32 v25, 0, v10, vcc
	v_cvt_pk_bf16_f32 v10, v12, v13
	v_cmp_le_i32_e32 vcc, v16, v26
	s_nop 1
	v_cndmask_b32_e32 v12, 0, v10, vcc
	v_lshrrev_b32_e32 v10, 16, v10
	v_cmp_le_i32_e32 vcc, v19, v26
	v_add_u32_e32 v26, 16, v26
	s_nop 0
	v_cndmask_b32_e32 v13, 0, v10, vcc
	v_lshl_add_u64 v[10:11], s[66:67], 0, v[20:21]
	v_add_co_u32_e32 v10, vcc, s0, v10
	s_mov_b64 s[0:1], 0x10000
	s_nop 0
	v_addc_co_u32_e32 v11, vcc, 0, v11, vcc
	v_perm_b32 v13, v13, v12, s59
	v_perm_b32 v12, v25, v24, s59
	v_lshl_add_u64 v[20:21], v[20:21], 0, s[0:1]
	v_lshl_add_u64 v[174:175], s[66:67], 0, v[22:23]
	global_load_dword v172, v[174:175], off
	global_store_dwordx2 v[10:11], v[28:29], off
	global_store_dwordx2 v[10:11], v[12:13], off offset:256
	s_cbranch_scc0 .LBB0_511
.LBB0_538:
	s_waitcnt vmcnt(2)
	v_mov_b32_e32 v29, v172
	v_add_u32_e32 v31, s4, v27
	ds_read_b32 v30, v31 offset:4
	ds_read_b64 v[24:25], v31 offset:8
	ds_read_b128 v[10:13], v31 offset:512
	v_cmp_le_i32_e32 vcc, v18, v26
	v_mov_b32_e32 v28, 0
	s_and_saveexec_b64 s[0:1], vcc
	s_cbranch_execz .LBB0_537
	s_waitcnt lgkmcnt(0)
	v_sub_f32_e32 v28, v2, v29
	v_mul_f32_e32 v28, 0x3fb8aa3b, v28
	ds_read_b32 v31, v31
	v_exp_f32_e32 v28, v28
	s_waitcnt lgkmcnt(0)
	v_mul_f32_e32 v28, v28, v31
	s_branch .LBB0_537

; __device__ __forceinline__ int ltid() { int t = threadIdx.x; asm volatile("" : "+v"(t)); return t; }
; __device__ __forceinline__ void emit_p(const float* stage, u16* dst, const float* aj, const float* Ai, int doff) {
;   const int tid = ltid(), c4 = (tid & 31) * 4, rr = tid >> 5;
;   const float4 a0 = *(const float4*)(aj + c4), a1 = *(const float4*)(aj + 128 + c4);
;   const float av[8] = {a0.x, a0.y, a0.z, a0.w, a1.x, a1.y, a1.z, a1.w};
; #pragma unroll 1
;   for (int ps = 0; ps < 8; ++ps) {
;     const int r = ps * 16 + rr;
;     const float* s = stage + r * SP + c4;
;     const float4 a = *(const float4*)s, b = *(const float4*)(s + 128);
;     float v[8] = {a.x, a.y, a.z, a.w, b.x, b.y, b.z, b.w};
;     const float A = Ai[r];
; #pragma unroll
;     for (int e = 0; e < 8; ++e) {
;       const int c = (e < 4) ? (c4 + e) : (128 + c4 + e - 4);
;       v[e] = (c <= r + doff) ? v[e] * __expf(av[e] - A) : 0.f;
;     }
;     uint2 o0, o1;
;     o0.x = pack2(v[0], v[1]); o0.y = pack2(v[2], v[3]); o1.x = pack2(v[4], v[5]); o1.y = pack2(v[6], v[7]);
;     *(uint2*)(dst + (long)r * 2048 + c4) = o0;
;     *(uint2*)(dst + (long)r * 2048 + 128 + c4) = o1;
;   }
; }
; template <int KIND>
; __device__ __forceinline__ void tile_emit(const Ctx& p, int t, int hd, int s, int half, const float* stage) {
;     ...
;   } else if (KIND == G_S) {
;     int tb, tc, ti, tj; s_decode(t, tb, tc, ti, tj);
;     const int bh = tb * 4 + hd;
;     const float* ga = (const float*)(ws + OFF_GA);
;     const float* gA = (const float*)(ws + OFF_GAA);
;     emit_p(stage, (u16*)(ws + OFF_PH) + (((long)tb * 4 + tc) * 2048 + ti * 256 + hr) * 2048 + tj * 256,
;            ga + bh * SEQ + tc * 2048 + tj * 256, gA + bh * SEQ + tc * 2048 + ti * 256 + hr, (ti - tj) * 256 + hr);
.LBB0_577:
	s_mov_b32 s8, s6
	s_mov_b32 s52, s7
	s_add_i32 s6, s5, 2
	s_add_i32 s7, s5, 3
	s_mul_i32 s6, s6, s7
	s_mov_b32 s9, s10
	s_lshr_b32 s11, s6, 1
	s_add_i32 s5, s5, 1
	s_add_i32 s6, s8, 1
	s_add_i32 s22, s1, 2
	s_add_i32 s10, s10, s1
	s_add_i32 s7, s52, 0x100
	s_cmp_le_i32 s11, s18
	s_mov_b32 s1, s22
	s_cbranch_scc1 .LBB0_577
	s_add_i32 s1, s5, 1
	s_mul_i32 s1, s1, s5
	s_lshr_b32 s1, s1, 1
	s_sext_i32_i16 s6, s4
	s_sub_i32 s4, s18, s1
	s_lshl_b32 s25, s0, 15
	s_lshl_b32 s28, s4, 8
	s_add_i32 s4, s25, s20
	s_ashr_i32 s1, s0, 31
	s_ashr_i32 s7, s6, 31
	s_ashr_i32 s5, s4, 31
	s_lshl_b64 s[10:11], s[0:1], 13
	s_lshl_b64 s[26:27], s[6:7], 11
	s_ashr_i32 s29, s28, 31
	s_lshl_b64 s[4:5], s[4:5], 2
	s_add_u32 s22, s14, s4
	s_addc_u32 s24, s15, s5
	s_lshl_b32 s4, s6, 11
	s_ashr_i32 s5, s4, 31
	s_lshl_b64 s[4:5], s[4:5], 2
	s_add_u32 s23, s22, s4
	v_mov_b32_e32 v84, v139
	s_addc_u32 s24, s24, s5
	s_lshl_b64 s[28:29], s[28:29], 2
	s_add_u32 s28, s23, s28
	v_lshlrev_b32_e32 v0, 2, v84
	v_and_b32_e32 v82, 0x7c, v0
	s_addc_u32 s29, s24, s29
	v_lshlrev_b32_e32 v0, 2, v82
	v_lshl_add_u64 v[2:3], s[28:29], 0, v[0:1]
	global_load_dwordx4 v[68:71], v[2:3], off
	global_load_dwordx4 v[72:75], v[2:3], off offset:512
	s_lshr_b32 s28, s9, 1
	v_ashrrev_i32_e32 v76, 5, v84
	s_add_i32 s8, s8, s28
	v_lshl_add_u32 v90, s8, 8, v76
	s_add_u32 s8, s10, s26
	s_addc_u32 s9, s11, s27
	s_add_u32 s8, s8, s52
	s_addc_u32 s9, s9, 0
	s_lshl_b32 s22, s18, 8
	s_lshl_b32 s10, s28, 8
	s_sub_i32 s10, s22, s10
	s_ashr_i32 s11, s10, 31
	v_ashrrev_i32_e32 v77, 31, v76
	s_lshl_b64 s[8:9], s[8:9], 12
	s_lshl_b64 s[10:11], s[10:11], 1
	v_lshlrev_b64 v[78:79], 12, v[76:77]
	v_and_b32_e32 v86, 31, v84
	s_add_u32 s8, s10, s8
	v_lshl_or_b32 v78, v86, 3, v78
	s_addc_u32 s9, s11, s9
	v_lshl_add_u64 v[84:85], s[8:9], 0, v[78:79]
	s_add_i32 s8, s17, s25
	s_ashr_i32 s9, s8, 31
	s_lshl_b64 s[8:9], s[8:9], 2
	s_lshl_b64 s[10:11], s[52:53], 2
	s_add_u32 s10, s10, s8
	s_addc_u32 s11, s11, s9
	s_add_u32 s10, s10, s4
	s_addc_u32 s11, s11, s5
	v_mul_lo_u32 v78, v76, s81
	v_lshlrev_b32_e32 v79, 4, v86
	v_lshl_add_u64 v[76:77], v[76:77], 2, s[10:11]
	s_mov_b64 s[10:11], 0x436c0000
	v_or_b32_e32 v3, 3, v82
	v_or_b32_e32 v0, 2, v82
	v_or_b32_e32 v81, 0x81, v82
	v_or_b32_e32 v2, 0x80, v82
	v_or_b32_e32 v83, 0x83, v82
	v_or_b32_e32 v80, 0x82, v82
	v_add3_u32 v91, v78, v79, 16
	v_lshl_add_u64 v[86:87], v[76:77], 0, s[10:11]
	s_mov_b32 s25, 0
	s_mov_b32 s28, 0xc400000
	v_lshl_add_u64 v[174:175], s[66:67], 0, v[86:87]
	global_load_dword v172, v[174:175], off
	s_waitcnt vmcnt(0)
	s_branch .LBB0_580
.LBB0_579:
	s_or_b64 exec, exec, s[10:11]
	s_waitcnt lgkmcnt(0)
	v_sub_f32_e32 v95, v69, v93
	v_mul_f32_e32 v95, 0x3fb8aa3b, v95
	v_exp_f32_e32 v95, v95
	v_cmp_lt_i32_e32 vcc, v82, v90
	s_addk_i32 s25, 0x4100
	s_mov_b64 s[10:11], 0x10000
	v_mul_f32_e32 v94, v94, v95
	v_cndmask_b32_e32 v96, 0, v94, vcc
	v_sub_f32_e32 v94, v70, v93
	v_sub_f32_e32 v95, v71, v93
	v_mul_f32_e32 v94, 0x3fb8aa3b, v94
	v_mul_f32_e32 v95, 0x3fb8aa3b, v95
	v_exp_f32_e32 v94, v94
	v_exp_f32_e32 v95, v95
	v_cmp_le_i32_e32 vcc, v0, v90
	v_cvt_pk_bf16_f32 v92, v92, v96
	v_lshl_add_u64 v[86:87], v[86:87], 0, 64
	v_pk_mul_f32 v[88:89], v[88:89], v[94:95]
	v_sub_f32_e32 v94, v72, v93
	v_sub_f32_e32 v95, v73, v93
	v_mul_f32_e32 v94, 0x3fb8aa3b, v94
	v_mul_f32_e32 v95, 0x3fb8aa3b, v95
	v_exp_f32_e32 v94, v94
	v_exp_f32_e32 v95, v95
	v_cvt_pk_bf16_f32 v88, v88, v89
	v_cndmask_b32_e32 v89, 0, v88, vcc
	v_lshrrev_b32_e32 v88, 16, v88
	v_pk_mul_f32 v[76:77], v[76:77], v[94:95]
	v_sub_f32_e32 v94, v74, v93
	v_sub_f32_e32 v93, v75, v93
	v_mul_f32_e32 v94, 0x3fb8aa3b, v94
	v_mul_f32_e32 v93, 0x3fb8aa3b, v93
	v_exp_f32_e32 v94, v94
	v_exp_f32_e32 v95, v93
	v_cmp_le_i32_e32 vcc, v3, v90
	v_cvt_pk_bf16_f32 v76, v76, v77
	s_cmp_lg_u32 s25, 0x20800
	v_cndmask_b32_e32 v88, 0, v88, vcc
	v_cmp_le_i32_e32 vcc, v2, v90
	v_pk_mul_f32 v[78:79], v[78:79], v[94:95]
	v_perm_b32 v93, v88, v89, s59
	v_cndmask_b32_e32 v88, 0, v76, vcc
	v_lshrrev_b32_e32 v76, 16, v76
	v_cmp_le_i32_e32 vcc, v81, v90
	s_nop 1
	v_cndmask_b32_e32 v89, 0, v76, vcc
	v_cvt_pk_bf16_f32 v76, v78, v79
	v_cmp_le_i32_e32 vcc, v80, v90
	s_nop 1
	v_cndmask_b32_e32 v78, 0, v76, vcc
	v_lshrrev_b32_e32 v76, 16, v76
	v_cmp_le_i32_e32 vcc, v83, v90
	v_add_u32_e32 v90, 16, v90
	s_nop 0
	v_cndmask_b32_e32 v79, 0, v76, vcc
	v_lshl_add_u64 v[76:77], s[66:67], 0, v[84:85]
	v_add_co_u32_e32 v76, vcc, s28, v76
	v_perm_b32 v79, v79, v78, s59
	s_nop 0
	v_addc_co_u32_e32 v77, vcc, 0, v77, vcc
	v_perm_b32 v78, v89, v88, s59
	v_lshl_add_u64 v[84:85], v[84:85], 0, s[10:11]
	v_lshl_add_u64 v[174:175], s[66:67], 0, v[86:87]
	global_load_dword v172, v[174:175], off
	global_store_dwordx2 v[76:77], v[92:93], off
	global_store_dwordx2 v[76:77], v[78:79], off offset:256
	s_cbranch_scc0 .LBB0_582
.LBB0_580:
	s_waitcnt vmcnt(2)
	v_mov_b32_e32 v93, v172
	v_add_u32_e32 v95, s25, v91
	ds_read_b32 v94, v95 offset:4
	ds_read_b64 v[88:89], v95 offset:8
	ds_read_b128 v[76:79], v95 offset:512
	v_cmp_le_i32_e32 vcc, v82, v90
	v_mov_b32_e32 v92, 0
	s_and_saveexec_b64 s[10:11], vcc
	s_cbranch_execz .LBB0_579
	s_waitcnt lgkmcnt(0)
	v_sub_f32_e32 v92, v68, v93
	v_mul_f32_e32 v92, 0x3fb8aa3b, v92
	ds_read_b32 v95, v95
	v_exp_f32_e32 v92, v92
	s_waitcnt lgkmcnt(0)
	v_mul_f32_e32 v92, v92, v95
	s_branch .LBB0_579

; __device__ __forceinline__ int ltid() { int t = threadIdx.x; asm volatile("" : "+v"(t)); return t; }
; __device__ __forceinline__ void emit_p(const float* stage, u16* dst, const float* aj, const float* Ai, int doff) {
;   const int tid = ltid(), c4 = (tid & 31) * 4, rr = tid >> 5;
;   const float4 a0 = *(const float4*)(aj + c4), a1 = *(const float4*)(aj + 128 + c4);
;   const float av[8] = {a0.x, a0.y, a0.z, a0.w, a1.x, a1.y, a1.z, a1.w};
; #pragma unroll 1
;   for (int ps = 0; ps < 8; ++ps) {
;     const int r = ps * 16 + rr;
;     const float* s = stage + r * SP + c4;
; template <int KIND>
; __device__ __forceinline__ void tile_emit(const Ctx& p, int t, int hd, int s, int half, const float* stage) {
;     ...
;   } else if (KIND == G_S) {
;     int tb, tc, ti, tj; s_decode(t, tb, tc, ti, tj);
;     const int bh = tb * 4 + hd;
;     const float* ga = (const float*)(ws + OFF_GA);
;     const float* gA = (const float*)(ws + OFF_GAA);
;     emit_p(stage, (u16*)(ws + OFF_PH) + (((long)tb * 4 + tc) * 2048 + ti * 256 + hr) * 2048 + tj * 256,
;            ga + bh * SEQ + tc * 2048 + tj * 256, gA + bh * SEQ + tc * 2048 + ti * 256 + hr, (ti - tj) * 256 + hr);
.LBB0_583:
	s_mov_b32 s11, s19
	s_mov_b32 s52, s27
	s_add_i32 s19, s26, 2
	s_add_i32 s27, s26, 3
	s_mul_i32 s19, s19, s27
	s_mov_b32 s25, s28
	s_lshr_b32 s29, s19, 1
	s_add_i32 s26, s26, 1
	s_add_i32 s19, s11, 1
	s_add_i32 s30, s10, 2
	s_add_i32 s28, s28, s10
	s_add_i32 s27, s52, 0x100
	s_cmp_le_i32 s29, s18
	s_mov_b32 s10, s30
	s_cbranch_scc1 .LBB0_583
	s_add_i32 s10, s26, 1
	s_mul_i32 s10, s10, s26
	s_lshr_b32 s10, s10, 1
	s_sub_i32 s10, s18, s10
	s_lshl_b32 s18, s10, 8
	s_ashr_i32 s19, s18, 31
	v_mov_b32_e32 v20, v139
	s_lshl_b64 s[18:19], s[18:19], 2
	s_add_u32 s18, s23, s18
	v_lshlrev_b32_e32 v0, 2, v20
	v_and_b32_e32 v18, 0x7c, v0
	s_addc_u32 s19, s24, s19
	v_lshlrev_b32_e32 v0, 2, v18
	v_lshl_add_u64 v[6:7], s[18:19], 0, v[0:1]
	global_load_dwordx4 v[2:5], v[6:7], off
	s_nop 0
	global_load_dwordx4 v[6:9], v[6:7], off offset:512
	s_lshr_b32 s10, s25, 1
	s_add_i32 s11, s11, s10
	s_lshl_b64 s[0:1], s[0:1], 25
	s_lshl_b64 s[6:7], s[6:7], 23
	v_ashrrev_i32_e32 v10, 5, v20
	s_add_u32 s0, s0, s6
	v_lshl_add_u32 v11, s11, 8, v10
	s_addc_u32 s1, s1, s7
	s_lshl_b32 s6, s10, 8
	v_add_u32_e32 v26, 0x80, v11
	v_ashrrev_i32_e32 v11, 31, v10
	s_sub_i32 s6, s22, s6
	v_lshlrev_b64 v[12:13], 12, v[10:11]
	s_ashr_i32 s7, s6, 31
	v_lshl_add_u64 v[12:13], s[0:1], 0, v[12:13]
	s_lshl_b64 s[0:1], s[52:53], 12
	s_lshl_b64 s[6:7], s[6:7], 1
	v_and_b32_e32 v22, 31, v20
	s_add_u32 s0, s6, s0
	v_lshl_or_b32 v12, v22, 3, v12
	s_addc_u32 s1, s7, s1
	v_lshl_add_u64 v[20:21], s[0:1], 0, v[12:13]
	s_lshl_b64 s[0:1], s[52:53], 2
	s_add_u32 s0, s0, s8
	s_addc_u32 s1, s1, s9
	s_add_u32 s0, s0, s4
	s_addc_u32 s1, s1, s5
	v_mul_lo_u32 v12, v10, s81
	v_lshlrev_b32_e32 v13, 4, v22
	v_lshl_add_u64 v[10:11], v[10:11], 2, s[0:1]
	s_mov_b64 s[0:1], 0x436c0200
	v_or_b32_e32 v15, 3, v18
	v_or_b32_e32 v0, 2, v18
	v_or_b32_e32 v17, 0x81, v18
	v_or_b32_e32 v14, 0x80, v18
	v_or_b32_e32 v19, 0x83, v18
	v_or_b32_e32 v16, 0x82, v18
	v_add3_u32 v27, v12, v13, 16
	v_lshl_add_u64 v[22:23], v[10:11], 0, s[0:1]
	s_mov_b32 s4, 0
	s_movk_i32 s52, 0x840
	v_lshl_add_u64 v[174:175], s[66:67], 0, v[22:23]
	global_load_dword v172, v[174:175], off
	s_waitcnt vmcnt(0)
	s_branch .LBB0_586
